# conv pass: staging loads of the 62-row window issued together (one wait) instead of load-wait-store per 16-byte chunk
# speedup vs baseline: 1.0152x; 1.0046x over previous
.LBB0_905:
	v_add_u32_e32 v4, s53, v20
	v_cmp_lt_i32_e32 vcc, -1, v4
	v_mov_b32_e32 v204, 0
	v_mov_b32_e32 v205, 0
	v_mov_b32_e32 v206, 0
	v_mov_b32_e32 v207, 0
	s_and_saveexec_b64 s[12:13], vcc
	s_cbranch_execz .LBB0_907
	v_add_u32_e32 v204, s52, v4
	v_ashrrev_i32_e32 v205, 31, v204
	v_lshlrev_b64 v[204:205], 10, v[204:205]
	v_lshl_add_u64 v[204:205], v[18:19], 0, v[204:205]
	global_load_dwordx4 v[204:207], v[204:205], off
.LBB0_907:
	s_or_b64 exec, exec, s[12:13]
	s_or_b64 exec, exec, s[0:1]
	s_and_saveexec_b64 s[0:1], s[8:9]
	s_cbranch_execz .LBB0_899
.LBB0_908:
	v_add_u32_e32 v4, s53, v24
	v_cmp_lt_i32_e32 vcc, -1, v4
	v_mov_b32_e32 v208, 0
	v_mov_b32_e32 v209, 0
	v_mov_b32_e32 v210, 0
	v_mov_b32_e32 v211, 0
	s_and_saveexec_b64 s[12:13], vcc
	s_cbranch_execz .LBB0_910
	v_add_u32_e32 v208, s52, v4
	v_ashrrev_i32_e32 v209, 31, v208
	v_lshlrev_b64 v[208:209], 10, v[208:209]
	v_lshl_add_u64 v[208:209], v[18:19], 0, v[208:209]
	global_load_dwordx4 v[208:211], v[208:209], off
.LBB0_910:
	s_or_b64 exec, exec, s[12:13]
	s_or_b64 exec, exec, s[0:1]
	s_and_saveexec_b64 s[0:1], s[14:15]
	s_cbranch_execz .LBB0_900
.LBB0_911:
	v_add_u32_e32 v4, s53, v26
	v_cmp_lt_i32_e32 vcc, -1, v4
	v_mov_b32_e32 v212, 0
	v_mov_b32_e32 v213, 0
	v_mov_b32_e32 v214, 0
	v_mov_b32_e32 v215, 0
	s_and_saveexec_b64 s[12:13], vcc
	s_cbranch_execz .LBB0_913
	v_add_u32_e32 v212, s52, v4
	v_ashrrev_i32_e32 v213, 31, v212
	v_lshlrev_b64 v[212:213], 10, v[212:213]
	v_lshl_add_u64 v[212:213], v[18:19], 0, v[212:213]
	global_load_dwordx4 v[212:215], v[212:213], off
.LBB0_913:
	s_or_b64 exec, exec, s[12:13]
	s_or_b64 exec, exec, s[0:1]
	s_and_saveexec_b64 s[0:1], s[20:21]
	s_cbranch_execz .LBB0_901
.LBB0_914:
	v_add_u32_e32 v4, s53, v28
	v_cmp_lt_i32_e32 vcc, -1, v4
	v_mov_b32_e32 v216, 0
	v_mov_b32_e32 v217, 0
	v_mov_b32_e32 v218, 0
	v_mov_b32_e32 v219, 0
	s_and_saveexec_b64 s[12:13], vcc
	s_cbranch_execz .LBB0_916
	v_add_u32_e32 v216, s52, v4
	v_ashrrev_i32_e32 v217, 31, v216
	v_lshlrev_b64 v[216:217], 10, v[216:217]
	v_lshl_add_u64 v[216:217], v[18:19], 0, v[216:217]
	global_load_dwordx4 v[216:219], v[216:217], off
.LBB0_916:
	s_or_b64 exec, exec, s[12:13]
	s_or_b64 exec, exec, s[0:1]
	s_and_saveexec_b64 s[0:1], s[26:27]
	s_cbranch_execz .LBB0_902
.LBB0_917:
	v_add_u32_e32 v4, s53, v30
	v_cmp_lt_i32_e32 vcc, -1, v4
	v_mov_b32_e32 v220, 0
	v_mov_b32_e32 v221, 0
	v_mov_b32_e32 v222, 0
	v_mov_b32_e32 v223, 0
	s_and_saveexec_b64 s[12:13], vcc
	s_cbranch_execz .LBB0_919
	v_add_u32_e32 v220, s52, v4
	v_ashrrev_i32_e32 v221, 31, v220
	v_lshlrev_b64 v[220:221], 10, v[220:221]
	v_lshl_add_u64 v[220:221], v[18:19], 0, v[220:221]
	global_load_dwordx4 v[220:223], v[220:221], off
.LBB0_919:
	s_or_b64 exec, exec, s[12:13]
	s_or_b64 exec, exec, s[0:1]
	s_and_saveexec_b64 s[0:1], s[34:35]
	s_cbranch_execz .LBB0_903
.LBB0_920:
	v_add_u32_e32 v4, s53, v32
	v_cmp_lt_i32_e32 vcc, -1, v4
	v_mov_b32_e32 v224, 0
	v_mov_b32_e32 v225, 0
	v_mov_b32_e32 v226, 0
	v_mov_b32_e32 v227, 0
	s_and_saveexec_b64 s[12:13], vcc
	s_cbranch_execz .LBB0_922
	v_add_u32_e32 v224, s52, v4
	v_ashrrev_i32_e32 v225, 31, v224
	v_lshlrev_b64 v[224:225], 10, v[224:225]
	v_lshl_add_u64 v[224:225], v[18:19], 0, v[224:225]
	global_load_dwordx4 v[224:227], v[224:225], off
.LBB0_922:
	s_or_b64 exec, exec, s[12:13]
	s_or_b64 exec, exec, s[0:1]
	s_and_saveexec_b64 s[0:1], s[36:37]
	s_cbranch_execz .LBB0_904
.LBB0_923:
	v_add_u32_e32 v4, s53, v34
	v_cmp_lt_i32_e32 vcc, -1, v4
	v_mov_b32_e32 v228, 0
	v_mov_b32_e32 v229, 0
	v_mov_b32_e32 v230, 0
	v_mov_b32_e32 v231, 0
	s_and_saveexec_b64 s[12:13], vcc
	s_cbranch_execz .LBB0_925
	v_add_u32_e32 v228, s52, v4
	v_ashrrev_i32_e32 v229, 31, v228
	v_lshlrev_b64 v[228:229], 10, v[228:229]
	v_lshl_add_u64 v[228:229], v[18:19], 0, v[228:229]
	global_load_dwordx4 v[228:231], v[228:229], off
.LBB0_925:
	s_or_b64 exec, exec, s[12:13]
	s_or_b64 exec, exec, s[0:1]
	s_and_saveexec_b64 s[0:1], s[38:39]
	s_cbranch_execz .LBB0_929
.LBB0_926:
	v_add_u32_e32 v4, s53, v36
	v_cmp_lt_i32_e32 vcc, -1, v4
	v_mov_b32_e32 v232, 0
	v_mov_b32_e32 v233, 0
	v_mov_b32_e32 v234, 0
	v_mov_b32_e32 v235, 0
	s_and_saveexec_b64 s[12:13], vcc
	s_cbranch_execz .LBB0_928
	v_add_u32_e32 v232, s52, v4
	v_ashrrev_i32_e32 v233, 31, v232
	v_lshlrev_b64 v[232:233], 10, v[232:233]
	v_lshl_add_u64 v[232:233], v[18:19], 0, v[232:233]
	global_load_dwordx4 v[232:235], v[232:233], off

.LBB0_929:
	s_or_b64 exec, exec, s[0:1]
	s_waitcnt vmcnt(0)
	s_and_saveexec_b64 s[0:1], s[2:3]
	v_add_u32_e32 v4, v106, v107
	ds_write_b128 v4, v[204:207]
	s_or_b64 exec, exec, s[0:1]
	s_and_saveexec_b64 s[0:1], s[8:9]
	v_add_u32_e32 v4, v106, v108
	ds_write_b128 v4, v[208:211]
	s_or_b64 exec, exec, s[0:1]
	s_and_saveexec_b64 s[0:1], s[14:15]
	v_add_u32_e32 v4, v106, v109
	ds_write_b128 v4, v[212:215]
	s_or_b64 exec, exec, s[0:1]
	s_and_saveexec_b64 s[0:1], s[20:21]
	v_add_u32_e32 v4, v106, v110
	ds_write_b128 v4, v[216:219]
	s_or_b64 exec, exec, s[0:1]
	s_and_saveexec_b64 s[0:1], s[26:27]
	v_add_u32_e32 v4, v106, v111
	ds_write_b128 v4, v[220:223]
	s_or_b64 exec, exec, s[0:1]
	s_and_saveexec_b64 s[0:1], s[34:35]
	v_add_u32_e32 v4, v106, v112
	ds_write_b128 v4, v[224:227]
	s_or_b64 exec, exec, s[0:1]
	s_and_saveexec_b64 s[0:1], s[36:37]
	v_add_u32_e32 v4, v106, v113
	ds_write_b128 v4, v[228:231]
	s_or_b64 exec, exec, s[0:1]
	s_and_saveexec_b64 s[0:1], s[38:39]
	v_add_u32_e32 v4, v106, v114
	ds_write_b128 v4, v[232:235]
	s_or_b64 exec, exec, s[0:1]
	s_lshl_b32 s12, s82, 5
	s_mov_b32 s13, 32
